# NORM_MLP row loop: next row's x prefetched into spare registers while the current row is reduced/normalised (stores no longer precede the next loads in the wait chain)
# baseline (speedup 1.0000x reference)
.LBB0_72:
	v_readlane_b32 s8, v254, 5
	s_cmpk_gt_i32 s22, 0x2fff
	v_readlane_b32 s9, v254, 6
	s_mov_b32 s7, 0x800000
	s_movk_i32 s10, 0x1000
	s_mov_b64 s[12:13], 0x1000
	s_cbranch_scc1 .LBB0_75
	v_and_b32_e32 v0, 64, v217
	v_add_u32_e32 v0, 64, v0
	s_waitcnt vmcnt(0)
	v_xor_b32_e32 v2, 1, v217
	v_cmp_lt_i32_e32 vcc, v2, v0
	s_load_dwordx4 s[16:19], s[48:49], 0x140
	s_add_u32 s4, s55, 0x3000
	v_cndmask_b32_e32 v2, v217, v2, vcc
	v_lshlrev_b32_e32 v6, 2, v2
	v_xor_b32_e32 v2, 2, v217
	v_cmp_lt_i32_e32 vcc, v2, v0
	s_addc_u32 s5, s3, 0
	s_ashr_i32 s23, s22, 31
	v_cndmask_b32_e32 v2, v217, v2, vcc
	v_lshlrev_b32_e32 v7, 2, v2
	v_xor_b32_e32 v2, 4, v217
	v_cmp_lt_i32_e32 vcc, v2, v0
	s_lshl_b64 s[0:1], s[22:23], 11
	s_waitcnt lgkmcnt(0)
	s_add_u32 s0, s18, s0
	v_cndmask_b32_e32 v2, v217, v2, vcc
	v_lshlrev_b32_e32 v8, 2, v2
	v_xor_b32_e32 v2, 8, v217
	v_cmp_lt_i32_e32 vcc, v2, v0
	s_addc_u32 s1, s19, s1
	s_mov_b32 s6, s22
	v_cndmask_b32_e32 v2, v217, v2, vcc
	v_lshlrev_b32_e32 v9, 2, v2
	v_xor_b32_e32 v2, 16, v217
	v_cmp_lt_i32_e32 vcc, v2, v0
	s_nop 1
	v_cndmask_b32_e32 v2, v217, v2, vcc
	v_lshlrev_b32_e32 v10, 2, v2
	v_xor_b32_e32 v2, 32, v217
	v_cmp_lt_i32_e32 vcc, v2, v0
	s_nop 1
	v_cndmask_b32_e32 v0, v217, v2, vcc
	v_lshlrev_b32_e32 v11, 2, v0
	v_lshlrev_b32_e32 v0, 3, v194
	v_lshl_add_u64 v[2:3], s[0:1], 0, v[0:1]
	s_mov_b64 s[0:1], 0x3500600
	v_lshl_add_u64 v[2:3], v[2:3], 0, s[0:1]
	s_lshl_b64 s[0:1], s[22:23], 12
	s_add_u32 s0, s16, s0
	v_lshlrev_b32_e32 v0, 4, v194
	s_addc_u32 s1, s17, s1
	v_lshl_add_u64 v[4:5], s[0:1], 0, v[0:1]
	s_mov_b64 s[0:1], 0x800
	v_lshl_add_u64 v[4:5], v[4:5], 0, s[0:1]
	v_lshlrev_b32_e32 v0, 4, v194
	global_load_dwordx4 v[100:103], v[4:5], off offset:-2048
	global_load_dwordx4 v[104:107], v[4:5], off offset:-1024
	global_load_dwordx4 v[108:111], v[4:5], off
	global_load_dwordx4 v[112:115], v[4:5], off offset:1024
	s_waitcnt vmcnt(0)
	v_mov_b64_e32 v[12:13], v[100:101]
	v_mov_b64_e32 v[14:15], v[102:103]
	v_mov_b64_e32 v[16:17], v[104:105]
	v_mov_b64_e32 v[18:19], v[106:107]
	v_mov_b64_e32 v[20:21], v[108:109]
	v_mov_b64_e32 v[22:23], v[110:111]
	v_mov_b64_e32 v[24:25], v[112:113]
	v_mov_b64_e32 v[26:27], v[114:115]
.LBB0_74:
	s_cmpk_lt_u32 s6, 0x2800
	s_cselect_b32 s0, s76, 0x3000
	s_cmpk_gt_i32 s6, 0x1fff
	s_cselect_b32 s0, s0, 0
	s_lshl_b32 s0, s0, 2
	s_add_u32 s0, s4, s0
	s_addc_u32 s1, s5, 0
	v_lshl_add_u64 v[84:85], s[0:1], 0, v[0:1]
	global_load_dwordx4 v[52:55], v0, s[0:1]
	v_lshl_add_u64 v[84:85], v[84:85], 0, s[12:13]
	s_add_i32 s6, s6, s70
	global_load_dwordx4 v[56:59], v[84:85], off
	global_load_dwordx4 v[60:63], v0, s[0:1] offset:1024
	global_load_dwordx4 v[64:67], v[84:85], off offset:1024
	global_load_dwordx4 v[68:71], v0, s[0:1] offset:2048
	global_load_dwordx4 v[72:75], v[84:85], off offset:2048
	global_load_dwordx4 v[76:79], v0, s[0:1] offset:3072
	global_load_dwordx4 v[80:83], v[84:85], off offset:3072
	s_cmpk_gt_i32 s6, 0x2fff
	s_cselect_b64 vcc, 0, s[96:97]
	s_nop 0
	v_lshl_add_u64 v[4:5], v[4:5], 0, vcc
	global_load_dwordx4 v[100:103], v[4:5], off offset:-2048
	global_load_dwordx4 v[104:107], v[4:5], off offset:-1024
	global_load_dwordx4 v[108:111], v[4:5], off
	global_load_dwordx4 v[112:115], v[4:5], off offset:1024
	v_pk_mul_f32 v[40:41], v[14:15], v[14:15]
	v_pk_mul_f32 v[42:43], v[12:13], v[12:13]
	s_nop 0
	v_pk_mov_b32 v[44:45], v[42:43], v[40:41] op_sel:[1,0]
	v_mov_b32_e32 v43, v41
	v_pk_add_f32 v[28:29], v[44:45], v[42:43]
	s_nop 0
	v_pk_add_f32 v[28:29], v[28:29], v[28:29] op_sel:[0,1] op_sel_hi:[1,0]
	v_pk_mul_f32 v[46:47], v[18:19], v[18:19]
	v_pk_mul_f32 v[48:49], v[16:17], v[16:17]
	s_nop 0
	v_pk_mov_b32 v[50:51], v[48:49], v[46:47] op_sel:[1,0]
	v_mov_b32_e32 v49, v47
	v_pk_add_f32 v[30:31], v[50:51], v[48:49]
	s_nop 0
	v_pk_add_f32 v[30:31], v[30:31], v[30:31] op_sel:[0,1] op_sel_hi:[1,0]
	v_mul_f32_e32 v32, v24, v24
	v_mul_f32_e32 v33, v25, v25
	v_mov_b32_e32 v29, v32
	v_mov_b32_e32 v31, v33
	v_pk_add_f32 v[28:29], v[28:29], v[30:31]
	v_mul_f32_e32 v30, v21, v21
	v_mul_f32_e32 v32, v23, v23
	v_mul_f32_e32 v34, v26, v26
	v_mul_f32_e32 v35, v27, v27
	v_pk_fma_f32 v[30:31], v[20:21], v[20:21], v[30:31] op_sel_hi:[1,1,0]
	v_pk_fma_f32 v[32:33], v[22:23], v[22:23], v[32:33] op_sel_hi:[1,1,0]
	v_mov_b32_e32 v31, v34
	v_mov_b32_e32 v33, v35
	v_pk_add_f32 v[30:31], v[30:31], v[32:33]
	s_nop 0
	v_pk_add_f32 v[28:29], v[28:29], v[30:31]
	s_nop 0
	v_add_f32_e32 v28, v28, v29
	ds_bpermute_b32 v29, v6, v28
	s_waitcnt lgkmcnt(0)
	v_add_f32_e32 v28, v28, v29
	ds_bpermute_b32 v29, v7, v28
	s_waitcnt lgkmcnt(0)
	v_add_f32_e32 v28, v28, v29
	ds_bpermute_b32 v29, v8, v28
	s_waitcnt lgkmcnt(0)
	v_add_f32_e32 v28, v28, v29
	ds_bpermute_b32 v29, v9, v28
	s_waitcnt lgkmcnt(0)
	v_add_f32_e32 v28, v28, v29
	ds_bpermute_b32 v29, v10, v28
	s_waitcnt lgkmcnt(0)
	v_add_f32_e32 v28, v28, v29
	ds_bpermute_b32 v29, v11, v28
	s_waitcnt lgkmcnt(0)
	v_add_f32_e32 v28, v28, v29
	v_fmamk_f32 v28, v28, 0x3a800000, v213
	v_cmp_gt_f32_e32 vcc, s7, v28
	v_mul_f32_e32 v29, 0x4b800000, v28
	s_nop 0
	v_cndmask_b32_e32 v28, v28, v29, vcc
	v_rsq_f32_e32 v28, v28
	s_nop 0
	v_mul_f32_e32 v29, 0x45800000, v28
	v_cndmask_b32_e32 v36, v28, v29, vcc
	v_pk_mul_f32 v[12:13], v[12:13], v[36:37] op_sel_hi:[1,0]
	v_pk_mul_f32 v[14:15], v[14:15], v[36:37] op_sel_hi:[1,0]
	v_pk_mul_f32 v[16:17], v[16:17], v[36:37] op_sel_hi:[1,0]
	v_pk_mul_f32 v[18:19], v[18:19], v[36:37] op_sel_hi:[1,0]
	v_pk_mul_f32 v[20:21], v[20:21], v[36:37] op_sel_hi:[1,0]
	v_pk_mul_f32 v[22:23], v[22:23], v[36:37] op_sel_hi:[1,0]
	v_pk_mul_f32 v[24:25], v[24:25], v[36:37] op_sel_hi:[1,0]
	v_pk_mul_f32 v[26:27], v[26:27], v[36:37] op_sel_hi:[1,0]
	s_waitcnt vmcnt(10)
	v_pk_add_f32 v[58:59], v[58:59], 1.0 op_sel_hi:[1,0]
	v_pk_add_f32 v[56:57], v[56:57], 1.0 op_sel_hi:[1,0]
	v_pk_fma_f32 v[34:35], v[58:59], v[14:15], v[54:55]
	v_pk_fma_f32 v[32:33], v[56:57], v[12:13], v[52:53]
	s_waitcnt vmcnt(8)
	v_pk_add_f32 v[66:67], v[66:67], 1.0 op_sel_hi:[1,0]
	v_pk_add_f32 v[64:65], v[64:65], 1.0 op_sel_hi:[1,0]
	v_pk_fma_f32 v[30:31], v[66:67], v[18:19], v[62:63]
	v_pk_fma_f32 v[28:29], v[64:65], v[16:17], v[60:61]
	s_waitcnt vmcnt(6)
	v_pk_add_f32 v[74:75], v[74:75], 1.0 op_sel_hi:[1,0]
	v_pk_add_f32 v[72:73], v[72:73], 1.0 op_sel_hi:[1,0]
	v_pk_fma_f32 v[22:23], v[74:75], v[22:23], v[70:71]
	v_pk_fma_f32 v[20:21], v[72:73], v[20:21], v[68:69]
	s_waitcnt vmcnt(4)
	v_pk_add_f32 v[80:81], v[80:81], 1.0 op_sel_hi:[1,0]
	v_pk_add_f32 v[82:83], v[82:83], 1.0 op_sel_hi:[1,0]
	v_pk_fma_f32 v[12:13], v[80:81], v[24:25], v[76:77]
	v_cvt_pk_bf16_f32 v16, v32, v33
	v_cvt_pk_bf16_f32 v17, v34, v35
	v_pk_fma_f32 v[14:15], v[82:83], v[26:27], v[78:79]
	global_store_dwordx2 v[2:3], v[16:17], off offset:-1536
	v_cvt_pk_bf16_f32 v18, v28, v29
	v_cvt_pk_bf16_f32 v19, v30, v31
	global_store_dwordx2 v[2:3], v[18:19], off offset:-1024
	v_cvt_pk_bf16_f32 v40, v20, v21
	v_cvt_pk_bf16_f32 v41, v22, v23
	v_cvt_pk_bf16_f32 v12, v12, v13
	v_cvt_pk_bf16_f32 v13, v14, v15
	global_store_dwordx2 v[2:3], v[40:41], off offset:-512
	global_store_dwordx2 v[2:3], v[12:13], off
	v_lshl_add_u64 v[2:3], v[2:3], 0, s[8:9]
	s_waitcnt vmcnt(4)
	v_mov_b64_e32 v[12:13], v[100:101]
	v_mov_b64_e32 v[14:15], v[102:103]
	v_mov_b64_e32 v[16:17], v[104:105]
	v_mov_b64_e32 v[18:19], v[106:107]
	v_mov_b64_e32 v[20:21], v[108:109]
	v_mov_b64_e32 v[22:23], v[110:111]
	v_mov_b64_e32 v[24:25], v[112:113]
	v_mov_b64_e32 v[26:27], v[114:115]
	s_cmpk_gt_i32 s6, 0x2fff
	s_cbranch_scc0 .LBB0_74
